# v15 plus attention prologue: hipcc vmcnt(0) glued to the first barrier relaxed (asm vmcnt(8) kept)
# speedup vs baseline: 1.0071x; 1.0010x over previous
; __device__ __forceinline__ int v_rd_base(int lane) { return ((lane & 3) << 3) | (((lane >> 2) & 3) << 6) | (((lane >> 4) & 1) << 5) | (((lane >> 5) & 1) << 8); }
; template <typename TQ>
; __device__ __forceinline__ void attn_dense_body(const TQ* __restrict__ Qb, const bf16* __restrict__ Kh, const bf16* __restrict__ Vh,
;                                                 bf16* __restrict__ Ob, int seq, char* lds, float mraw) {
;     ...
;   const TQ* Qw = Qb + (long)(wid * QBLK + r32) * LDQ + hi * 8;
; #pragma unroll
;   for (int d0 = 0; d0 < 8; ++d0) qr[d0] = SQ::tobf(SQ::ld8(Qw + d0 * 16));
;   long ksrc[2], vsrc[2];
; #pragma unroll
;   for (int t = 0; t < 2; ++t) { const int q = (wid * 2 + t) * 64 + lane;
;     { const int row = q >> 4, c = (q & 15) ^ (row & 7); ksrc[t] = (long)row * LDK + c * 8; }
;     { const int off = q * 16, sub = off >> 9, kk = (sub >> 2) * 8 + ((off & 511) >> 6), cc = (sub & 3) * 32 + ((off & 63) >> 1);
;       const int k = (kk & ~0xC) | ((kk & 4) << 1) | ((kk & 8) >> 1); vsrc[t] = (long)k * LDK + cc; } }
;   const int vb0 = (int)ldsb + v_rd_base(lane);
;     ...
;   f32x16 pA0, pA1, pB0, pB1; bf16x8 pa0, pa1, pa2, pa3; const int NT = seq / KVBLK;
;   DMA_TILE(0, 0); DMA_TILE(1, 1); DMA_TILE(2, 2);
;   asm volatile("s_waitcnt vmcnt(8)" ::: "memory"); __syncthreads();
.LBB0_610:
	s_ashr_i32 s11, s10, 31
	s_lshl_b64 s[16:17], s[10:11], 8
	s_add_u32 s16, s16, 0x100
	s_addc_u32 s17, s17, 0
	s_and_b64 s[6:7], s[6:7], exec
	s_mul_i32 s18, s14, 0x1100
	s_cselect_b32 s6, 0, s16
	s_mul_hi_i32 s12, s14, 0x1100
	s_cselect_b32 s11, 4, 0x44
	s_cselect_b32 s7, 0, s17
	s_add_u32 s6, s18, s6
	s_addc_u32 s7, s12, s7
	s_mul_i32 s12, s7, 0xc00
	s_mul_hi_u32 s16, s6, 0xc00
	s_add_i32 s16, s16, s12
	s_mul_i32 s12, s6, 0xc00
	s_add_u32 s12, s1, s12
	s_addc_u32 s18, s2, s16
	s_lshl_b32 s16, s15, 7
	s_ashr_i32 s17, s16, 31
	s_lshl_b64 s[20:21], s[16:17], 1
	s_add_u32 s22, s12, s20
	s_addc_u32 s23, s18, s21
	s_mul_i32 s16, s14, 0xcc0000
	s_mul_hi_i32 s12, s14, 0xcc0000
	s_add_u32 s18, s1, s16
	s_addc_u32 s12, s2, s12
	s_lshl_b32 s16, s15, 5
	s_and_b32 s16, s16, 0xffffff80
	s_ashr_i32 s17, s16, 31
	s_lshl_b64 s[58:59], s[16:17], 1
	v_mov_b32_e32 v179, v242
	s_barrier
	s_add_u32 s52, s18, s58
	s_addc_u32 s53, s12, s59
	v_readfirstlane_b32 s16, v179
	s_ashr_i32 s12, s16, 6
	v_and_b32_e32 v180, 31, v179
	s_lshl_b32 s18, s12, 5
	v_bfe_u32 v181, v179, 5, 1
	s_waitcnt lgkmcnt(0)
	v_or_b32_e32 v18, s18, v180
	v_mov_b64_e32 v[16:17], s[22:23]
	s_movk_i32 s50, 0xc00
	v_mad_i64_i32 v[16:17], s[22:23], v18, s50, v[16:17]
	v_lshlrev_b32_e32 v128, 4, v181
	v_lshl_add_u64 v[16:17], v[16:17], 0, v[128:129]
	global_load_dwordx4 v[158:161], v[16:17], off
	global_load_dwordx4 v[154:157], v[16:17], off offset:32
	global_load_dwordx4 v[150:153], v[16:17], off offset:64
	global_load_dwordx4 v[146:149], v[16:17], off offset:96
	global_load_dwordx4 v[142:145], v[16:17], off offset:128
	global_load_dwordx4 v[138:141], v[16:17], off offset:160
	global_load_dwordx4 v[134:137], v[16:17], off offset:192
	global_load_dwordx4 v[130:133], v[16:17], off offset:224
	s_lshl_b32 s17, s12, 7
	v_and_b32_e32 v182, 63, v179
	s_ashr_i32 s19, s17, 4
	v_or_b32_e32 v40, s17, v182
	s_and_b32 s17, s19, -16
	s_lshr_b32 s19, s19, 1
	v_and_b32_e32 v22, 15, v179
	s_and_b32 s24, s19, 4
	v_ashrrev_i32_e32 v41, 4, v40
	s_movk_i32 s25, 0x600
	v_lshrrev_b32_e32 v18, 1, v179
	s_or_b32 s19, s24, s17
	v_bitop3_b32 v42, v41, v22, 3 bitop3:0x6c
	v_mad_i64_i32 v[16:17], s[22:23], v41, s25, 0
	v_and_b32_e32 v44, 8, v18
	v_bfe_u32 v45, v179, 2, 2
	v_or_b32_e32 v48, 64, v40
	v_lshl_or_b32 v16, v42, 3, v16
	v_or3_b32 v18, v45, v44, s19
	v_lshlrev_b32_e32 v46, 3, v182
	v_ashrrev_i32_e32 v49, 4, v48
	s_movk_i32 s19, 0x60
	s_cmp_lg_u32 0, -1
	v_and_b32_e32 v43, 32, v179
	v_mad_i64_i32 v[18:19], s[22:23], v18, s25, 0
	v_and_b32_e32 v47, 24, v46
	v_bitop3_b32 v50, v49, v22, 7 bitop3:0x6c
	v_mad_i64_i32 v[22:23], s[22:23], v49, s25, 0
	v_bitop3_b32 v24, v40, s19, 64 bitop3:0xc8
	s_cselect_b32 s28, 0, 0
	v_lshlrev_b64 v[16:17], 1, v[16:17]
	v_or3_b32 v20, v47, v43, v18
	v_mov_b32_e32 v21, v19
	v_or3_b32 v18, v47, v24, v18
	s_lshl_b32 s19, s12, 11
	v_lshl_add_u64 v[24:25], s[52:53], 0, v[16:17]
	s_mov_b64 s[22:23], 0x800
	s_add_i32 s12, s28, 0xc000
	v_lshl_add_u64 v[24:25], v[24:25], 0, s[22:23]
	s_add_i32 m0, s19, s12
	v_lshlrev_b64 v[20:21], 1, v[20:21]
	v_lshl_or_b32 v22, v50, 3, v22
	global_load_lds_dwordx4 v[24:25], off
	v_lshl_add_u64 v[24:25], s[52:53], 0, v[20:21]
	s_mov_b64 s[26:27], 0xa00
	v_lshl_add_u64 v[24:25], v[24:25], 0, s[26:27]
	s_add_i32 m0, s19, s28
	v_lshlrev_b64 v[22:23], 1, v[22:23]
	global_load_lds_dwordx4 v[24:25], off
	v_lshl_add_u64 v[24:25], s[52:53], 0, v[22:23]
	v_lshl_add_u64 v[24:25], v[24:25], 0, s[22:23]
	s_or_b32 s22, s19, 0x400
	s_add_i32 m0, s22, s12
	v_lshlrev_b64 v[18:19], 1, v[18:19]
	global_load_lds_dwordx4 v[24:25], off
	v_lshl_add_u64 v[24:25], s[52:53], 0, v[18:19]
	s_add_i32 m0, s22, s28
	v_lshl_add_u64 v[24:25], v[24:25], 0, s[26:27]
	s_add_u32 s26, s52, 0x30800
	s_addc_u32 s27, s53, 0
	s_add_u32 s38, s52, 0x30a00
	s_addc_u32 s39, s53, 0
	s_add_i32 s12, s28, 0x10000
	global_load_lds_dwordx4 v[24:25], off
	v_lshl_add_u64 v[24:25], s[26:27], 0, v[16:17]
	s_add_i32 m0, s19, s12
	s_add_i32 s23, s28, 0x4000
	global_load_lds_dwordx4 v[24:25], off
	v_lshl_add_u64 v[24:25], s[38:39], 0, v[20:21]
	s_add_i32 m0, s19, s23
	v_lshlrev_b32_e32 v51, 8, v180
	global_load_lds_dwordx4 v[24:25], off
	v_lshl_add_u64 v[24:25], s[26:27], 0, v[22:23]
	s_add_i32 m0, s22, s12
	s_mov_b32 s25, 0
	global_load_lds_dwordx4 v[24:25], off
	s_add_i32 m0, s22, s23
	s_add_u32 s26, s52, 0x60800
	s_addc_u32 s27, s53, 0
	v_lshl_add_u64 v[24:25], s[38:39], 0, v[18:19]
	s_add_u32 s38, s52, 0x60a00
	s_addc_u32 s39, s53, 0
	s_add_i32 s12, s28, 0x14000
	global_load_lds_dwordx4 v[24:25], off
	v_lshl_add_u64 v[16:17], s[26:27], 0, v[16:17]
	s_add_i32 m0, s19, s12
	s_add_i32 s23, s28, 0x8000
	global_load_lds_dwordx4 v[16:17], off
	v_lshl_add_u64 v[16:17], s[38:39], 0, v[20:21]
	s_add_i32 m0, s19, s23
	s_nop 0
	global_load_lds_dwordx4 v[16:17], off
	v_lshl_add_u64 v[16:17], s[26:27], 0, v[22:23]
	s_add_i32 m0, s22, s12
	s_movk_i32 s26, 0xc0
	global_load_lds_dwordx4 v[16:17], off
	v_lshl_add_u64 v[16:17], s[38:39], 0, v[18:19]
	s_add_i32 m0, s22, s23
	v_readlane_b32 s38, v254, 33
	global_load_lds_dwordx4 v[16:17], off
	v_lshlrev_b32_e32 v16, 4, v179
	v_and_b32_e32 v52, 0x70, v16
	v_bitop3_b32 v203, v128, v51, v52 bitop3:0xde
	v_add_u32_e32 v16, 0, v203
	s_waitcnt vmcnt(8)
	s_waitcnt lgkmcnt(0)
	s_barrier
; __device__ __forceinline__ void qkt(f32x16& p0, f32x16& p1, const bf16* Ks, const bf16x8* qr, int r32, int hi, const f32x16& iv) {
; #pragma unroll
;   for (int d0 = 0; d0 < 8; ++d0) { int cb = (d0 * 16 + hi * 8) * 2;
;     bf16x8 b0 = *reinterpret_cast<const bf16x8*>((const char*)Ks + KSWZ(r32, cb));
;     bf16x8 b1 = *reinterpret_cast<const bf16x8*>((const char*)Ks + KSWZ(32 + r32, cb));
;     p0 = __builtin_amdgcn_mfma_f32_32x32x16_bf16(b0, qr[d0], d0 == 0 ? iv : p0, 0, 0, 0);
;     p1 = __builtin_amdgcn_mfma_f32_32x32x16_bf16(b1, qr[d0], d0 == 0 ? iv : p1, 0, 0, 0); }
; template <typename TQ>
; __device__ __forceinline__ void attn_dense_body(const TQ* __restrict__ Qb, const bf16* __restrict__ Kh, const bf16* __restrict__ Vh,
;                                                 bf16* __restrict__ Ob, int seq, char* lds, float mraw) {
;     ...
;   qkt(pA0, pA1, KBUF(0), qr, r32, hi, iv); partialSM_fixed(pA0, pA1, mnC);
;   asm volatile("s_waitcnt vmcnt(4)" ::: "memory"); __syncthreads();
;   int bprev = 0, bcur = 1, bnext = 2;
	ds_read_b128 v[32:35], v16 offset:49152
	ds_read_b128 v[36:39], v16 offset:57344
	s_waitcnt lgkmcnt(1)
	v_mfma_f32_32x32x16_bf16 v[16:31], v[32:35], v[158:161], v[0:15]
	v_or_b32_e32 v32, 32, v128
	v_bitop3_b32 v204, v32, v51, v52 bitop3:0xde
	s_mov_b32 s23, 4
	s_mov_b32 s12, 1
	s_waitcnt lgkmcnt(0)
	v_mfma_f32_32x32x16_bf16 v[80:95], v[36:39], v[158:161], v[0:15]
	v_add_u32_e32 v36, 0, v204
	ds_read_b128 v[32:35], v36 offset:49152
	ds_read_b128 v[36:39], v36 offset:57344
	s_waitcnt lgkmcnt(1)
	v_mfma_f32_32x32x16_bf16 v[16:31], v[32:35], v[154:157], v[16:31]
	v_or_b32_e32 v32, 64, v128
	v_bitop3_b32 v206, v32, v51, v52 bitop3:0xde
	s_waitcnt lgkmcnt(0)
	v_mfma_f32_32x32x16_bf16 v[80:95], v[36:39], v[154:157], v[80:95]
	v_add_u32_e32 v36, 0, v206
	ds_read_b128 v[32:35], v36 offset:49152
	ds_read_b128 v[36:39], v36 offset:57344
	s_waitcnt lgkmcnt(1)
	v_mfma_f32_32x32x16_bf16 v[16:31], v[32:35], v[150:153], v[16:31]
	v_or_b32_e32 v32, 0x60, v128
	v_bitop3_b32 v207, v32, v51, v52 bitop3:0xde
	s_waitcnt lgkmcnt(0)
	v_mfma_f32_32x32x16_bf16 v[80:95], v[36:39], v[150:153], v[80:95]
	v_add_u32_e32 v36, 0, v207
	ds_read_b128 v[32:35], v36 offset:49152
	ds_read_b128 v[36:39], v36 offset:57344
	s_waitcnt lgkmcnt(1)
	v_mfma_f32_32x32x16_bf16 v[16:31], v[32:35], v[146:149], v[16:31]
	v_or_b32_e32 v32, 0x80, v128
	v_bitop3_b32 v208, v32, v51, v52 bitop3:0xde
	s_waitcnt lgkmcnt(0)
	v_mfma_f32_32x32x16_bf16 v[80:95], v[36:39], v[146:149], v[80:95]
	v_add_u32_e32 v36, 0, v208
	ds_read_b128 v[32:35], v36 offset:49152
	ds_read_b128 v[36:39], v36 offset:57344
	s_waitcnt lgkmcnt(1)
	v_mfma_f32_32x32x16_bf16 v[16:31], v[32:35], v[142:145], v[16:31]
	v_or_b32_e32 v32, 0xa0, v128
	v_bitop3_b32 v205, v32, v51, v52 bitop3:0xde
	s_waitcnt lgkmcnt(0)
	v_mfma_f32_32x32x16_bf16 v[80:95], v[36:39], v[142:145], v[80:95]
	v_add_u32_e32 v36, 0, v205
	ds_read_b128 v[32:35], v36 offset:49152
	ds_read_b128 v[36:39], v36 offset:57344
	s_waitcnt lgkmcnt(1)
	v_mfma_f32_32x32x16_bf16 v[16:31], v[32:35], v[138:141], v[16:31]
	v_or_b32_e32 v32, 0xc0, v128
	v_bitop3_b32 v202, v32, v51, v52 bitop3:0xde
	s_waitcnt lgkmcnt(0)
	v_mfma_f32_32x32x16_bf16 v[80:95], v[36:39], v[138:141], v[80:95]
	v_add_u32_e32 v36, 0, v202
	ds_read_b128 v[32:35], v36 offset:49152
	ds_read_b128 v[36:39], v36 offset:57344
	s_waitcnt lgkmcnt(1)
	v_mfma_f32_32x32x16_bf16 v[16:31], v[32:35], v[134:137], v[16:31]
	v_or_b32_e32 v32, 0xe0, v128
	v_bitop3_b32 v200, v32, v51, v52 bitop3:0xde
	s_waitcnt lgkmcnt(0)
	v_mfma_f32_32x32x16_bf16 v[80:95], v[36:39], v[134:137], v[80:95]
	v_add_u32_e32 v36, 0, v200
	ds_read_b128 v[32:35], v36 offset:49152
	ds_read_b128 v[36:39], v36 offset:57344
	s_waitcnt vmcnt(4)
	s_waitcnt lgkmcnt(0)
	s_barrier
	v_mfma_f32_32x32x16_bf16 v[16:31], v[32:35], v[130:133], v[16:31]
	v_lshlrev_b32_e32 v32, 4, v182
	v_and_or_b32 v33, v32, s26, v47
	v_lshlrev_b32_e32 v34, 1, v179
	v_and_b32_e32 v34, 32, v34
	v_and_b32_e32 v35, 0x100, v46
	v_or3_b32 v33, v33, v34, v35
	v_add_u32_e32 v199, s28, v33
	s_nop 4
	v_exp_f32_e32 v211, v16
	v_bitop3_b32 v16, v40, 3, 64 bitop3:0xc8
	v_exp_f32_e32 v215, v18
	v_lshlrev_b32_e32 v18, 4, v16
	v_lshlrev_b32_e32 v16, 1, v48
	v_exp_f32_e32 v216, v19
	v_and_b32_e32 v19, 0xc0, v16
	v_or_b32_e32 v16, s17, v44
	v_or3_b32 v16, v16, s24, v45
	v_exp_f32_e32 v214, v17
	v_mad_i64_i32 v[16:17], s[26:27], v16, s50, 0
	v_mad_i64_i32 v[16:17], s[26:27], s14, v236, v[16:17]
	v_or3_b32 v18, v19, v18, v16
	v_mov_b32_e32 v19, v17
	v_lshl_add_u64 v[162:163], s[8:9], 0, v[18:19]
	v_lshlrev_b32_e32 v18, 1, v43
	v_and_b32_e32 v19, 48, v32
	v_or3_b32 v16, v19, v18, v16
	v_lshl_add_u64 v[164:165], s[8:9], 0, v[16:17]
	v_mad_i64_i32 v[16:17], s[26:27], v49, s50, 0
	v_mad_i64_i32 v[16:17], s[26:27], s14, v236, v[16:17]
	v_lshl_or_b32 v16, v50, 4, v16
	v_lshl_add_u64 v[166:167], s[8:9], 0, v[16:17]
	v_mad_i64_i32 v[16:17], s[26:27], v41, s50, 0
	v_mad_i64_i32 v[16:17], s[26:27], s14, v236, v[16:17]
	v_lshl_or_b32 v16, v42, 4, v16
	v_mov_b32_e32 v48, 0
	v_mfma_f32_32x32x16_bf16 v[80:95], v[36:39], v[130:133], v[80:95]
	v_exp_f32_e32 v217, v20
	v_exp_f32_e32 v218, v21
	v_exp_f32_e32 v209, v22
	v_exp_f32_e32 v213, v23
	v_exp_f32_e32 v173, v24
	v_exp_f32_e32 v175, v25
	v_exp_f32_e32 v176, v26
	v_exp_f32_e32 v177, v27
	v_exp_f32_e32 v170, v28
	v_exp_f32_e32 v171, v29
	v_exp_f32_e32 v172, v30
	v_exp_f32_e32 v174, v31
	v_lshl_add_u64 v[168:169], s[8:9], 0, v[16:17]
	s_mov_b32 s17, 2
	v_mov_b32_e32 v49, v48
	v_mov_b32_e32 v50, v48
	v_mov_b32_e32 v51, v48
	v_mov_b32_e32 v52, v48
	v_mov_b32_e32 v53, v48
	v_mov_b32_e32 v54, v48
	v_mov_b32_e32 v55, v48
	v_mov_b32_e32 v56, v48
	v_mov_b32_e32 v57, v48
	v_mov_b32_e32 v58, v48
	v_mov_b32_e32 v59, v48
	v_mov_b32_e32 v60, v48
	v_mov_b32_e32 v61, v48
	v_mov_b32_e32 v62, v48
	v_mov_b32_e32 v63, v48
	v_mov_b32_e32 v64, v48
	v_mov_b32_e32 v65, v48
	v_mov_b32_e32 v66, v48
	v_mov_b32_e32 v67, v48
	v_mov_b32_e32 v68, v48
	v_mov_b32_e32 v69, v48
	v_mov_b32_e32 v70, v48
	v_mov_b32_e32 v71, v48
	v_mov_b32_e32 v72, v48
	v_mov_b32_e32 v73, v48
	v_mov_b32_e32 v74, v48
	v_mov_b32_e32 v75, v48
	v_mov_b32_e32 v76, v48
	v_mov_b32_e32 v77, v48
	v_mov_b32_e32 v78, v48
	v_mov_b32_e32 v79, v48
	v_mov_b32_e32 v32, v48
	v_mov_b32_e32 v33, v48
	v_mov_b32_e32 v34, v48
	v_mov_b32_e32 v35, v48
	v_mov_b32_e32 v36, v48
	v_mov_b32_e32 v37, v48
	v_mov_b32_e32 v38, v48
	v_mov_b32_e32 v39, v48
	v_mov_b32_e32 v40, v48
	v_mov_b32_e32 v41, v48
	v_mov_b32_e32 v42, v48
	v_mov_b32_e32 v43, v48
	v_mov_b32_e32 v44, v48
	v_mov_b32_e32 v45, v48
	v_mov_b32_e32 v46, v48
	v_mov_b32_e32 v47, v48
	v_mov_b32_e32 v16, v48
	v_mov_b32_e32 v17, v48
	v_mov_b32_e32 v18, v48
	v_mov_b32_e32 v19, v48
	v_mov_b32_e32 v20, v48
	v_mov_b32_e32 v21, v48
	v_mov_b32_e32 v22, v48
	v_mov_b32_e32 v23, v48
	v_mov_b32_e32 v24, v48
	v_mov_b32_e32 v25, v48
	v_mov_b32_e32 v26, v48
	v_mov_b32_e32 v27, v48
	v_mov_b32_e32 v28, v48
	v_mov_b32_e32 v29, v48
	v_mov_b32_e32 v30, v48
	v_mov_b32_e32 v31, v48
	v_mov_b32_e32 v194, v48
	v_mov_b32_e32 v195, v48
	v_mov_b32_e32 v196, v48
	v_mov_b32_e32 v197, v48
	v_mov_b32_e32 v198, v48
	v_mov_b32_e32 v187, v48
	v_mov_b32_e32 v188, v48
	v_mov_b32_e32 v189, v48
	v_mov_b32_e32 v190, v48
	v_mov_b32_e32 v191, v48
	v_mov_b32_e32 v192, v48
	v_mov_b32_e32 v193, v48
	v_mov_b32_e32 v183, v48
	v_mov_b32_e32 v184, v48
	v_mov_b32_e32 v185, v48
	v_mov_b32_e32 v186, v48
